# mixB sample item (MIX1 long pole on 16 workgroups): all W/bias loads hoisted ahead of the interleaved stores; mixB prompt bias loads hoisted
# speedup vs baseline: 1.0052x; 1.0029x over previous
.LBB0_636:
	s_or_b64 exec, exec, s[20:21]
	v_lshlrev_b32_e32 v60, 7, v158
	s_add_u32 s18, s18, s10
	v_or_b32_e32 v50, v60, v171
	s_addc_u32 s19, s19, s11
	v_ashrrev_i32_e32 v51, 31, v50
	v_lshl_add_u64 v[48:49], v[50:51], 2, s[18:19]
	global_load_dword v51, v[48:49], off
	global_load_dword v63, v[48:49], off offset:64
	global_load_dword v64, v[48:49], off offset:128
	global_load_dword v65, v[48:49], off offset:192
	v_lshlrev_b32_e32 v58, 2, v170
	v_lshlrev_b32_e32 v184, 1, v58
	s_waitcnt vmcnt(19)
	v_lshlrev_b32_e32 v58, 16, v166
	v_or_b32_e32 v56, s23, v171
	v_mov_b64_e32 v[48:49], s[12:13]
	v_mad_i64_i32 v[56:57], s[20:21], v56, s68, v[48:49]
	v_lshl_add_u64 v[56:57], v[56:57], 0, s[96:97]
	v_lshl_add_u64 v[56:57], v[56:57], 0, v[140:141]
	v_lshl_add_u64 v[56:57], v[56:57], 0, v[184:185]
	s_waitcnt vmcnt(0)
	v_add_f32_e32 v59, v84, v51
	v_mul_f32_e32 v58, v59, v58
	v_and_b32_e32 v59, 0xffff0000, v166
	v_add_f32_e32 v61, v85, v51
	v_mul_f32_e32 v59, v61, v59
	v_cvt_pk_bf16_f32 v58, v58, v59
	v_lshlrev_b32_e32 v59, 16, v167
	v_add_f32_e32 v61, v86, v51
	v_mul_f32_e32 v59, v61, v59
	v_and_b32_e32 v61, 0xffff0000, v167
	v_add_f32_e32 v62, v87, v51
	v_mul_f32_e32 v61, v62, v61
	v_cvt_pk_bf16_f32 v59, v59, v61
	global_store_dwordx2 v[56:57], v[58:59], off offset:2048
	v_lshlrev_b32_e32 v58, 16, v164
	v_add_f32_e32 v59, v80, v51
	v_mul_f32_e32 v58, v59, v58
	v_and_b32_e32 v59, 0xffff0000, v164
	v_add_f32_e32 v61, v81, v51
	v_mul_f32_e32 v59, v61, v59
	v_cvt_pk_bf16_f32 v58, v58, v59
	v_lshlrev_b32_e32 v59, 16, v165
	v_add_f32_e32 v61, v82, v51
	v_mul_f32_e32 v59, v61, v59
	v_and_b32_e32 v61, 0xffff0000, v165
	v_add_f32_e32 v62, v83, v51
	v_mul_f32_e32 v61, v62, v61
	v_cvt_pk_bf16_f32 v59, v59, v61
	global_store_dwordx2 v[56:57], v[58:59], off offset:2080
	v_lshlrev_b32_e32 v58, 16, v162
	v_add_f32_e32 v59, v76, v51
	v_mul_f32_e32 v58, v59, v58
	v_and_b32_e32 v59, 0xffff0000, v162
	v_add_f32_e32 v61, v77, v51
	v_mul_f32_e32 v59, v61, v59
	v_cvt_pk_bf16_f32 v58, v58, v59
	v_lshlrev_b32_e32 v59, 16, v163
	v_add_f32_e32 v61, v78, v51
	v_mul_f32_e32 v59, v61, v59
	v_and_b32_e32 v61, 0xffff0000, v163
	v_add_f32_e32 v62, v79, v51
	v_mul_f32_e32 v61, v62, v61
	v_cvt_pk_bf16_f32 v59, v59, v61
	global_store_dwordx2 v[56:57], v[58:59], off offset:2112
	v_lshlrev_b32_e32 v58, 16, v160
	v_add_f32_e32 v52, v52, v51
	v_mul_f32_e32 v52, v52, v58
	v_and_b32_e32 v58, 0xffff0000, v160
	v_add_f32_e32 v53, v53, v51
	v_mul_f32_e32 v53, v53, v58
	v_cvt_pk_bf16_f32 v52, v52, v53
	v_lshlrev_b32_e32 v53, 16, v161
	v_add_f32_e32 v54, v54, v51
	v_mul_f32_e32 v53, v54, v53
	v_and_b32_e32 v54, 0xffff0000, v161
	v_add_f32_e32 v51, v55, v51
	v_mul_f32_e32 v51, v51, v54
	v_cvt_pk_bf16_f32 v53, v53, v51
	v_ashrrev_i32_e32 v51, 31, v60
	global_store_dwordx2 v[56:57], v[52:53], off offset:2144
	v_lshl_add_u64 v[50:51], v[50:51], 2, s[18:19]
	v_mov_b32_e32 v54, v63
	v_or_b32_e32 v52, s23, v159
	v_lshlrev_b32_e32 v55, 16, v156
	v_mad_i64_i32 v[52:53], s[18:19], v52, s68, v[48:49]
	v_lshl_add_u64 v[52:53], v[52:53], 0, s[96:97]
	v_lshl_add_u64 v[52:53], v[52:53], 0, v[140:141]
	v_lshl_add_u64 v[52:53], v[52:53], 0, v[184:185]
	v_add_f32_e32 v32, v32, v54
	v_mul_f32_e32 v32, v32, v55
	v_and_b32_e32 v55, 0xffff0000, v156
	v_add_f32_e32 v33, v33, v54
	v_mul_f32_e32 v33, v33, v55
	v_cvt_pk_bf16_f32 v32, v32, v33
	v_lshlrev_b32_e32 v33, 16, v157
	v_add_f32_e32 v34, v34, v54
	v_mul_f32_e32 v33, v34, v33
	v_and_b32_e32 v34, 0xffff0000, v157
	v_add_f32_e32 v35, v35, v54
	v_mul_f32_e32 v34, v35, v34
	v_cvt_pk_bf16_f32 v33, v33, v34
	global_store_dwordx2 v[52:53], v[32:33], off offset:2048
	v_lshlrev_b32_e32 v32, 16, v154
	v_add_f32_e32 v28, v28, v54
	v_mul_f32_e32 v28, v28, v32
	v_and_b32_e32 v32, 0xffff0000, v154
	v_add_f32_e32 v29, v29, v54
	v_mul_f32_e32 v29, v29, v32
	v_cvt_pk_bf16_f32 v28, v28, v29
	v_lshlrev_b32_e32 v29, 16, v155
	v_add_f32_e32 v30, v30, v54
	v_mul_f32_e32 v29, v30, v29
	v_and_b32_e32 v30, 0xffff0000, v155
	v_add_f32_e32 v31, v31, v54
	v_mul_f32_e32 v30, v31, v30
	v_cvt_pk_bf16_f32 v29, v29, v30
	global_store_dwordx2 v[52:53], v[28:29], off offset:2080
	v_lshlrev_b32_e32 v28, 16, v152
	v_add_f32_e32 v24, v24, v54
	v_mul_f32_e32 v24, v24, v28
	v_and_b32_e32 v28, 0xffff0000, v152
	v_add_f32_e32 v25, v25, v54
	v_mul_f32_e32 v25, v25, v28
	v_cvt_pk_bf16_f32 v24, v24, v25
	v_lshlrev_b32_e32 v25, 16, v153
	v_add_f32_e32 v26, v26, v54
	v_mul_f32_e32 v25, v26, v25
	v_and_b32_e32 v26, 0xffff0000, v153
	v_add_f32_e32 v27, v27, v54
	v_mul_f32_e32 v26, v27, v26
	v_cvt_pk_bf16_f32 v25, v25, v26
	global_store_dwordx2 v[52:53], v[24:25], off offset:2112
	v_lshlrev_b32_e32 v24, 16, v150
	v_add_f32_e32 v16, v16, v54
	v_mul_f32_e32 v16, v16, v24
	v_and_b32_e32 v24, 0xffff0000, v150
	v_add_f32_e32 v17, v17, v54
	v_mul_f32_e32 v17, v17, v24
	v_cvt_pk_bf16_f32 v16, v16, v17
	v_lshlrev_b32_e32 v17, 16, v151
	v_add_f32_e32 v18, v18, v54
	v_mul_f32_e32 v17, v18, v17
	v_and_b32_e32 v18, 0xffff0000, v151
	v_add_f32_e32 v19, v19, v54
	v_mul_f32_e32 v18, v19, v18
	v_cvt_pk_bf16_f32 v17, v17, v18
	global_store_dwordx2 v[52:53], v[16:17], off offset:2144
	v_mov_b32_e32 v24, v64
	v_lshlrev_b32_e32 v18, 16, v148
	v_or_b32_e32 v16, s23, v169
	v_mad_i64_i32 v[16:17], s[18:19], v16, s68, v[48:49]
	v_lshl_add_u64 v[16:17], v[16:17], 0, s[96:97]
	v_lshl_add_u64 v[16:17], v[16:17], 0, v[140:141]
	v_lshl_add_u64 v[16:17], v[16:17], 0, v[184:185]
	v_add_f32_e32 v19, v44, v24
	v_mul_f32_e32 v18, v19, v18
	v_and_b32_e32 v19, 0xffff0000, v148
	v_add_f32_e32 v25, v45, v24
	v_mul_f32_e32 v19, v25, v19
	v_cvt_pk_bf16_f32 v18, v18, v19
	v_lshlrev_b32_e32 v19, 16, v149
	v_add_f32_e32 v25, v46, v24
	v_mul_f32_e32 v19, v25, v19
	v_and_b32_e32 v25, 0xffff0000, v149
	v_add_f32_e32 v26, v47, v24
	v_mul_f32_e32 v25, v26, v25
	v_cvt_pk_bf16_f32 v19, v19, v25
	global_store_dwordx2 v[16:17], v[18:19], off offset:2048
	v_lshlrev_b32_e32 v18, 16, v146
	v_add_f32_e32 v19, v40, v24
	v_mul_f32_e32 v18, v19, v18
	v_and_b32_e32 v19, 0xffff0000, v146
	v_add_f32_e32 v25, v41, v24
	v_mul_f32_e32 v19, v25, v19
	v_cvt_pk_bf16_f32 v18, v18, v19
	v_lshlrev_b32_e32 v19, 16, v147
	v_add_f32_e32 v25, v42, v24
	v_mul_f32_e32 v19, v25, v19
	v_and_b32_e32 v25, 0xffff0000, v147
	v_add_f32_e32 v26, v43, v24
	v_mul_f32_e32 v25, v26, v25
	v_cvt_pk_bf16_f32 v19, v19, v25
	global_store_dwordx2 v[16:17], v[18:19], off offset:2080
	v_lshlrev_b32_e32 v18, 16, v144
	v_add_f32_e32 v19, v36, v24
	v_mul_f32_e32 v18, v19, v18
	v_and_b32_e32 v19, 0xffff0000, v144
	v_add_f32_e32 v25, v37, v24
	v_mul_f32_e32 v19, v25, v19
	v_cvt_pk_bf16_f32 v18, v18, v19
	v_lshlrev_b32_e32 v19, 16, v145
	v_add_f32_e32 v25, v38, v24
	v_mul_f32_e32 v19, v25, v19
	v_and_b32_e32 v25, 0xffff0000, v145
	v_add_f32_e32 v26, v39, v24
	v_mul_f32_e32 v25, v26, v25
	v_cvt_pk_bf16_f32 v19, v19, v25
	global_store_dwordx2 v[16:17], v[18:19], off offset:2112
	v_lshlrev_b32_e32 v18, 16, v142
	v_add_f32_e32 v19, v20, v24
	v_mul_f32_e32 v18, v19, v18
	v_and_b32_e32 v19, 0xffff0000, v142
	v_add_f32_e32 v20, v21, v24
	v_mul_f32_e32 v19, v20, v19
	v_cvt_pk_bf16_f32 v18, v18, v19
	v_lshlrev_b32_e32 v19, 16, v143
	v_add_f32_e32 v20, v22, v24
	v_mul_f32_e32 v19, v20, v19
	v_and_b32_e32 v20, 0xffff0000, v143
	v_add_f32_e32 v21, v23, v24
	v_mul_f32_e32 v20, v21, v20
	v_cvt_pk_bf16_f32 v19, v19, v20
	global_store_dwordx2 v[16:17], v[18:19], off offset:2144
	v_mov_b32_e32 v18, v65
	v_or_b32_e32 v16, s23, v104
	v_lshlrev_b32_e32 v19, 16, v138
	v_mad_i64_i32 v[16:17], s[18:19], v16, s68, v[48:49]
	v_lshl_add_u64 v[16:17], v[16:17], 0, s[96:97]
	v_lshl_add_u64 v[16:17], v[16:17], 0, v[140:141]
	v_lshl_add_u64 v[16:17], v[16:17], 0, v[184:185]
	v_add_f32_e32 v12, v12, v18
	v_mul_f32_e32 v12, v12, v19
	v_and_b32_e32 v19, 0xffff0000, v138
	v_add_f32_e32 v13, v13, v18
	v_mul_f32_e32 v13, v13, v19
	v_cvt_pk_bf16_f32 v12, v12, v13
	v_lshlrev_b32_e32 v13, 16, v139
	v_add_f32_e32 v14, v14, v18
	v_mul_f32_e32 v13, v14, v13
	v_and_b32_e32 v14, 0xffff0000, v139
	v_add_f32_e32 v15, v15, v18
	v_mul_f32_e32 v14, v15, v14
	v_cvt_pk_bf16_f32 v13, v13, v14
	global_store_dwordx2 v[16:17], v[12:13], off offset:2048
	v_lshlrev_b32_e32 v12, 16, v136
	v_add_f32_e32 v8, v8, v18
	v_mul_f32_e32 v8, v8, v12
	v_and_b32_e32 v12, 0xffff0000, v136
	v_add_f32_e32 v9, v9, v18
	v_mul_f32_e32 v9, v9, v12
	v_cvt_pk_bf16_f32 v8, v8, v9
	v_lshlrev_b32_e32 v9, 16, v137
	v_add_f32_e32 v10, v10, v18
	v_mul_f32_e32 v9, v10, v9
	v_and_b32_e32 v10, 0xffff0000, v137
	v_add_f32_e32 v11, v11, v18
	v_mul_f32_e32 v10, v11, v10
	v_cvt_pk_bf16_f32 v9, v9, v10
	global_store_dwordx2 v[16:17], v[8:9], off offset:2080
	v_lshlrev_b32_e32 v8, 16, v134
	v_add_f32_e32 v4, v4, v18
	v_mul_f32_e32 v4, v4, v8
	v_and_b32_e32 v8, 0xffff0000, v134
	v_add_f32_e32 v5, v5, v18
	v_mul_f32_e32 v5, v5, v8
	v_cvt_pk_bf16_f32 v4, v4, v5
	v_lshlrev_b32_e32 v5, 16, v135
	v_add_f32_e32 v6, v6, v18
	v_mul_f32_e32 v5, v6, v5
	v_and_b32_e32 v6, 0xffff0000, v135
	v_add_f32_e32 v7, v7, v18
	v_mul_f32_e32 v6, v7, v6
	v_cvt_pk_bf16_f32 v5, v5, v6
	global_store_dwordx2 v[16:17], v[4:5], off offset:2112
	v_lshlrev_b32_e32 v4, 16, v132
	v_add_f32_e32 v0, v0, v18
	v_mul_f32_e32 v0, v0, v4
	v_and_b32_e32 v4, 0xffff0000, v132
	v_add_f32_e32 v1, v1, v18
	v_mul_f32_e32 v1, v1, v4
	v_cvt_pk_bf16_f32 v0, v0, v1
	v_lshlrev_b32_e32 v1, 16, v133
	v_add_f32_e32 v2, v2, v18
	v_mul_f32_e32 v1, v2, v1
	v_and_b32_e32 v2, 0xffff0000, v133
	v_add_f32_e32 v3, v3, v18
	v_mul_f32_e32 v2, v3, v2
	v_cvt_pk_bf16_f32 v1, v1, v2
	global_store_dwordx2 v[16:17], v[0:1], off offset:2144
	s_barrier

.LBB0_638:
	s_cmpk_gt_i32 s22, 0xff
	s_mov_b64 s[18:19], -1
	s_cbranch_scc0 .LBB0_640
	v_mov_b32_e32 v46, v195
	s_movk_i32 s18, 0x200
	v_ashrrev_i32_e32 v0, 6, v46
	v_add_u32_e32 v1, s3, v0
	v_ashrrev_i32_e32 v44, 1, v1
	v_lshlrev_b32_e32 v1, 3, v46
	v_lshlrev_b32_e32 v0, 9, v0
	v_and_b32_e32 v1, 0x1f8, v1
	v_and_or_b32 v45, v0, s18, v1
	v_lshlrev_b32_e32 v32, 3, v44
	v_lshlrev_b32_e32 v184, 1, v45
	v_add_u32_e32 v115, 0x2000, v32
	v_lshl_add_u64 v[0:1], s[12:13], 0, v[184:185]
	v_mad_i64_i32 v[2:3], s[18:19], v115, s68, v[0:1]
	v_add_co_u32_e32 v4, vcc, 0x1000, v2
	v_add_u32_e32 v114, 0x2001, v32
	s_nop 0
	v_addc_co_u32_e32 v5, vcc, 0, v3, vcc
	global_load_dwordx4 v[52:55], v[4:5], off
	global_load_dwordx4 v[28:31], v[2:3], off offset:2048
	v_mad_i64_i32 v[2:3], s[18:19], v114, s68, v[0:1]
	v_add_co_u32_e32 v4, vcc, 0x1000, v2
	v_add_u32_e32 v125, 0x2002, v32
	s_nop 0
	v_addc_co_u32_e32 v5, vcc, 0, v3, vcc
	global_load_dwordx4 v[60:63], v[4:5], off
	global_load_dwordx4 v[24:27], v[2:3], off offset:2048
	v_mad_i64_i32 v[2:3], s[18:19], v125, s68, v[0:1]
	v_add_co_u32_e32 v4, vcc, 0x1000, v2
	v_add_u32_e32 v124, 0x2003, v32
	s_nop 0
	v_addc_co_u32_e32 v5, vcc, 0, v3, vcc
	global_load_dwordx4 v[36:39], v[4:5], off
	global_load_dwordx4 v[20:23], v[2:3], off offset:2048
	v_mad_i64_i32 v[2:3], s[18:19], v124, s68, v[0:1]
	v_add_co_u32_e32 v4, vcc, 0x1000, v2
	v_add_u32_e32 v131, 0x2004, v32
	s_nop 0
	v_addc_co_u32_e32 v5, vcc, 0, v3, vcc
	global_load_dwordx4 v[64:67], v[4:5], off
	global_load_dwordx4 v[16:19], v[2:3], off offset:2048
	v_mad_i64_i32 v[2:3], s[18:19], v131, s68, v[0:1]
	v_add_co_u32_e32 v4, vcc, 0x1000, v2
	v_add_u32_e32 v130, 0x2005, v32
	s_nop 0
	v_addc_co_u32_e32 v5, vcc, 0, v3, vcc
	global_load_dwordx4 v[56:59], v[4:5], off
	global_load_dwordx4 v[12:15], v[2:3], off offset:2048
	v_mad_i64_i32 v[2:3], s[18:19], v130, s68, v[0:1]
	v_add_co_u32_e32 v4, vcc, 0x1000, v2
	v_add_u32_e32 v129, 0x2006, v32
	s_nop 0
	v_addc_co_u32_e32 v5, vcc, 0, v3, vcc
	global_load_dwordx4 v[48:51], v[4:5], off
	global_load_dwordx4 v[8:11], v[2:3], off offset:2048
	v_mad_i64_i32 v[2:3], s[18:19], v129, s68, v[0:1]
	v_add_co_u32_e32 v4, vcc, 0x1000, v2
	v_add_u32_e32 v128, 0x2007, v32
	v_and_or_b32 v46, v46, 7, v115
	v_addc_co_u32_e32 v5, vcc, 0, v3, vcc
	v_mad_i64_i32 v[0:1], s[18:19], v128, s68, v[0:1]
	v_ashrrev_i32_e32 v47, 31, v46
	global_load_dwordx4 v[40:43], v[4:5], off
	s_nop 0
	global_load_dwordx4 v[4:7], v[2:3], off offset:2048
	v_add_co_u32_e32 v2, vcc, 0x1000, v0
	v_lshlrev_b64 v[46:47], 7, v[46:47]
	s_nop 0
	v_addc_co_u32_e32 v3, vcc, 0, v1, vcc
	v_lshl_add_u64 v[46:47], s[14:15], 0, v[46:47]
	global_load_dwordx4 v[32:35], v[2:3], off
	s_nop 0
	global_load_dwordx4 v[0:3], v[0:1], off offset:2048
	s_nop 0
	global_load_dwordx4 v[68:71], v[46:47], off offset:48
	global_load_dwordx4 v[72:75], v[46:47], off offset:32
	global_load_dwordx4 v[76:79], v[46:47], off offset:16
	global_load_dwordx4 v[80:83], v[46:47], off
	global_load_dwordx4 v[84:87], v[46:47], off offset:112
	global_load_dwordx4 v[88:91], v[46:47], off offset:96
	global_load_dwordx4 v[92:95], v[46:47], off offset:80
	global_load_dwordx4 v[96:99], v[46:47], off offset:64
	s_load_dwordx8 s[72:79], s[80:81], 0xa0
	s_mov_b32 s18, 0x3a800000
	v_add_u32_e32 v44, s0, v44
	s_waitcnt lgkmcnt(0)
	v_mov_b32_e32 v110, s78
	v_mov_b32_e32 v111, s79
	s_waitcnt vmcnt(20)
	v_lshlrev_b32_e32 v127, 16, v26
	v_and_b32_e32 v26, 0xffff0000, v26
	v_lshlrev_b32_e32 v132, 16, v27
	v_and_b32_e32 v27, 0xffff0000, v27
	s_waitcnt vmcnt(7)
	v_pk_add_f32 v[68:69], v[68:69], v[70:71]
	s_waitcnt vmcnt(6)
	v_pk_add_f32 v[72:73], v[72:73], v[74:75]
	s_waitcnt vmcnt(5)
	v_pk_add_f32 v[76:77], v[76:77], v[78:79]
	s_waitcnt vmcnt(4)
	v_pk_add_f32 v[46:47], v[80:81], v[82:83]
	v_lshlrev_b32_e32 v78, 16, v60
	v_pk_add_f32 v[46:47], v[46:47], 0 op_sel_hi:[1,0]
	v_and_b32_e32 v79, 0xffff0000, v60
	v_pk_add_f32 v[46:47], v[46:47], v[76:77]
	v_lshlrev_b32_e32 v60, 16, v61
	v_pk_add_f32 v[46:47], v[46:47], v[72:73]
	v_and_b32_e32 v61, 0xffff0000, v61
	v_pk_add_f32 v[46:47], v[46:47], v[68:69]
	s_waitcnt vmcnt(0)
	v_pk_add_f32 v[68:69], v[96:97], v[98:99]
	s_nop 0
	v_pk_add_f32 v[46:47], v[46:47], v[68:69]
	v_pk_add_f32 v[68:69], v[92:93], v[94:95]
	s_nop 0
	v_pk_add_f32 v[46:47], v[46:47], v[68:69]
	v_pk_add_f32 v[68:69], v[88:89], v[90:91]
	s_nop 0
	v_pk_add_f32 v[46:47], v[46:47], v[68:69]
	v_pk_add_f32 v[68:69], v[84:85], v[86:87]
	s_nop 0
	v_pk_add_f32 v[46:47], v[46:47], v[68:69]
	s_nop 0
	v_pk_mul_f32 v[108:109], v[46:47], s[18:19] op_sel_hi:[1,0]
	s_lshl_b64 s[18:19], s[6:7], 2
	v_fma_f32 v46, -v108, v108, v109
	s_add_u32 s20, s72, s18
	v_max_f32_e32 v46, 0, v46
	s_addc_u32 s21, s73, s19
	v_add_f32_e32 v72, 0x358637bd, v46
	v_lshlrev_b32_e32 v46, 2, v45
	s_add_u32 s18, s74, s18
	s_addc_u32 s19, s75, s19
	global_load_dwordx4 v[84:87], v46, s[20:21] offset:16
	global_load_dwordx4 v[68:71], v46, s[20:21]
	global_load_dwordx4 v[88:91], v46, s[18:19] offset:16
	global_load_dwordx4 v[92:95], v46, s[18:19]
	s_load_dwordx2 s[18:19], s[80:81], 0xf8
	v_ashrrev_i32_e32 v45, 31, v44
	v_lshlrev_b64 v[44:45], 15, v[44:45]
	v_mov_b32_e32 v47, v185
	v_rsq_f32_e32 v109, v72
	s_waitcnt lgkmcnt(0)
	v_lshl_add_u64 v[44:45], s[18:19], 0, v[44:45]
	v_lshl_add_u64 v[112:113], v[44:45], 0, v[46:47]
	v_lshlrev_b32_e32 v44, 2, v221
	v_and_b32_e32 v119, 0x100, v44
	ds_bpermute_b32 v74, v119, v108
	ds_bpermute_b32 v76, v119, v109
	s_mov_b64 s[18:19], 0x4a60000
	v_lshlrev_b32_e32 v44, 16, v52
	v_and_b32_e32 v45, 0xffff0000, v52
	v_lshlrev_b32_e32 v46, 16, v53
	v_and_b32_e32 v47, 0xffff0000, v53
	v_lshl_add_u64 v[72:73], v[112:113], 0, s[18:19]
	s_waitcnt lgkmcnt(1)
	v_pk_add_f32 v[44:45], v[44:45], v[74:75] op_sel_hi:[1,0] neg_lo:[0,1] neg_hi:[0,1]
	v_pk_add_f32 v[46:47], v[46:47], v[74:75] op_sel_hi:[1,0] neg_lo:[0,1] neg_hi:[0,1]
	v_lshlrev_b32_e32 v52, 16, v54
	v_and_b32_e32 v53, 0xffff0000, v54
	v_lshlrev_b32_e32 v54, 16, v55
	v_and_b32_e32 v55, 0xffff0000, v55
	s_mov_b32 s18, 0x4a61000
	s_waitcnt lgkmcnt(0)
	v_pk_mul_f32 v[44:45], v[44:45], v[76:77] op_sel_hi:[1,0]
	v_pk_mul_f32 v[46:47], v[46:47], v[76:77] op_sel_hi:[1,0]
	v_pk_add_f32 v[52:53], v[52:53], v[74:75] op_sel_hi:[1,0] neg_lo:[0,1] neg_hi:[0,1]
	v_pk_add_f32 v[54:55], v[54:55], v[74:75] op_sel_hi:[1,0] neg_lo:[0,1] neg_hi:[0,1]
	v_add_co_u32_e32 v74, vcc, s18, v112
	v_pk_mul_f32 v[52:53], v[52:53], v[76:77] op_sel_hi:[1,0]
	v_pk_mul_f32 v[54:55], v[54:55], v[76:77] op_sel_hi:[1,0]
	v_addc_co_u32_e32 v75, vcc, 0, v113, vcc
	ds_bpermute_b32 v76, v119, v109 offset:4
	s_mov_b32 s18, 0x4a62000
	ds_bpermute_b32 v118, v119, v109 offset:20
	s_waitcnt vmcnt(1)
	v_pk_fma_f32 v[52:53], v[84:85], v[52:53], v[88:89]
	s_waitcnt vmcnt(0)
	v_pk_fma_f32 v[44:45], v[68:69], v[44:45], v[92:93]
	v_pk_fma_f32 v[46:47], v[70:71], v[46:47], v[94:95]
	v_pk_fma_f32 v[54:55], v[86:87], v[54:55], v[90:91]
	global_store_dwordx4 v[74:75], v[44:47], off offset:-4096
	global_store_dwordx4 v[72:73], v[52:55], off offset:16
	ds_bpermute_b32 v72, v119, v108 offset:4
	s_waitcnt lgkmcnt(0)
	v_pk_add_f32 v[60:61], v[60:61], v[72:73] op_sel_hi:[1,0] neg_lo:[0,1] neg_hi:[0,1]
	s_nop 0
	v_pk_mul_f32 v[60:61], v[60:61], v[76:77] op_sel_hi:[1,0]
	v_pk_add_f32 v[78:79], v[78:79], v[72:73] op_sel_hi:[1,0] neg_lo:[0,1] neg_hi:[0,1]
	v_pk_fma_f32 v[106:107], v[70:71], v[60:61], v[94:95]
	v_lshlrev_b32_e32 v60, 16, v62
	v_and_b32_e32 v61, 0xffff0000, v62
	v_lshlrev_b32_e32 v62, 16, v63
	v_and_b32_e32 v63, 0xffff0000, v63
	v_pk_mul_f32 v[78:79], v[78:79], v[76:77] op_sel_hi:[1,0]
	v_pk_add_f32 v[60:61], v[60:61], v[72:73] op_sel_hi:[1,0] neg_lo:[0,1] neg_hi:[0,1]
	v_pk_add_f32 v[62:63], v[62:63], v[72:73] op_sel_hi:[1,0] neg_lo:[0,1] neg_hi:[0,1]
	v_pk_fma_f32 v[104:105], v[68:69], v[78:79], v[92:93]
	v_pk_mul_f32 v[60:61], v[60:61], v[76:77] op_sel_hi:[1,0]
	v_pk_mul_f32 v[62:63], v[62:63], v[76:77] op_sel_hi:[1,0]
	ds_bpermute_b32 v72, v119, v108 offset:8
	v_pk_fma_f32 v[60:61], v[84:85], v[60:61], v[88:89]
	v_pk_fma_f32 v[62:63], v[86:87], v[62:63], v[90:91]
	global_store_dwordx4 v[74:75], v[104:107], off
	global_store_dwordx4 v[74:75], v[60:63], off offset:16
	ds_bpermute_b32 v74, v119, v109 offset:8
	v_lshlrev_b32_e32 v76, 16, v36
	v_and_b32_e32 v77, 0xffff0000, v36
	v_lshlrev_b32_e32 v36, 16, v37
	v_and_b32_e32 v37, 0xffff0000, v37
	s_waitcnt lgkmcnt(1)
	v_pk_add_f32 v[36:37], v[36:37], v[72:73] op_sel_hi:[1,0] neg_lo:[0,1] neg_hi:[0,1]
	v_pk_add_f32 v[76:77], v[76:77], v[72:73] op_sel_hi:[1,0] neg_lo:[0,1] neg_hi:[0,1]
	s_waitcnt lgkmcnt(0)
	v_pk_mul_f32 v[36:37], v[36:37], v[74:75] op_sel_hi:[1,0]
	v_pk_mul_f32 v[76:77], v[76:77], v[74:75] op_sel_hi:[1,0]
	v_pk_fma_f32 v[102:103], v[70:71], v[36:37], v[94:95]
	v_lshlrev_b32_e32 v36, 16, v38
	v_and_b32_e32 v37, 0xffff0000, v38
	v_lshlrev_b32_e32 v38, 16, v39
	v_and_b32_e32 v39, 0xffff0000, v39
	v_pk_add_f32 v[36:37], v[36:37], v[72:73] op_sel_hi:[1,0] neg_lo:[0,1] neg_hi:[0,1]
	v_pk_add_f32 v[38:39], v[38:39], v[72:73] op_sel_hi:[1,0] neg_lo:[0,1] neg_hi:[0,1]
	v_add_co_u32_e32 v72, vcc, s18, v112
	s_mov_b32 s18, 0x4a63000
	s_nop 0
	v_addc_co_u32_e32 v73, vcc, 0, v113, vcc
	v_pk_mul_f32 v[36:37], v[36:37], v[74:75] op_sel_hi:[1,0]
	v_pk_mul_f32 v[38:39], v[38:39], v[74:75] op_sel_hi:[1,0]
	v_add_co_u32_e32 v74, vcc, s18, v112
	v_pk_fma_f32 v[100:101], v[68:69], v[76:77], v[92:93]
	s_nop 0
	v_addc_co_u32_e32 v75, vcc, 0, v113, vcc
	v_pk_fma_f32 v[36:37], v[84:85], v[36:37], v[88:89]
	v_pk_fma_f32 v[38:39], v[86:87], v[38:39], v[90:91]
	global_store_dwordx4 v[74:75], v[100:103], off offset:-4096
	global_store_dwordx4 v[72:73], v[36:39], off offset:16
	ds_bpermute_b32 v72, v119, v108 offset:12
	ds_bpermute_b32 v76, v119, v109 offset:12
	v_lshlrev_b32_e32 v78, 16, v64
	v_and_b32_e32 v79, 0xffff0000, v64
	v_lshlrev_b32_e32 v64, 16, v65
	v_and_b32_e32 v65, 0xffff0000, v65
	s_waitcnt lgkmcnt(1)
	v_pk_add_f32 v[64:65], v[64:65], v[72:73] op_sel_hi:[1,0] neg_lo:[0,1] neg_hi:[0,1]
	v_pk_add_f32 v[78:79], v[78:79], v[72:73] op_sel_hi:[1,0] neg_lo:[0,1] neg_hi:[0,1]
	s_waitcnt lgkmcnt(0)
	v_pk_mul_f32 v[64:65], v[64:65], v[76:77] op_sel_hi:[1,0]
	v_pk_mul_f32 v[78:79], v[78:79], v[76:77] op_sel_hi:[1,0]
	v_pk_fma_f32 v[98:99], v[70:71], v[64:65], v[94:95]
	v_lshlrev_b32_e32 v64, 16, v66
	v_and_b32_e32 v65, 0xffff0000, v66
	v_lshlrev_b32_e32 v66, 16, v67
	v_and_b32_e32 v67, 0xffff0000, v67
	v_pk_add_f32 v[64:65], v[64:65], v[72:73] op_sel_hi:[1,0] neg_lo:[0,1] neg_hi:[0,1]
	v_pk_add_f32 v[66:67], v[66:67], v[72:73] op_sel_hi:[1,0] neg_lo:[0,1] neg_hi:[0,1]
	v_pk_fma_f32 v[96:97], v[68:69], v[78:79], v[92:93]
	v_pk_mul_f32 v[64:65], v[64:65], v[76:77] op_sel_hi:[1,0]
	v_pk_mul_f32 v[66:67], v[66:67], v[76:77] op_sel_hi:[1,0]
	ds_bpermute_b32 v72, v119, v108 offset:16
	v_pk_fma_f32 v[64:65], v[84:85], v[64:65], v[88:89]
	v_pk_fma_f32 v[66:67], v[86:87], v[66:67], v[90:91]
	global_store_dwordx4 v[74:75], v[96:99], off
	global_store_dwordx4 v[74:75], v[64:67], off offset:16
	ds_bpermute_b32 v74, v119, v109 offset:16
	v_lshlrev_b32_e32 v76, 16, v56
	v_and_b32_e32 v77, 0xffff0000, v56
	v_lshlrev_b32_e32 v56, 16, v57
	v_and_b32_e32 v57, 0xffff0000, v57
	s_waitcnt lgkmcnt(1)
	v_pk_add_f32 v[56:57], v[56:57], v[72:73] op_sel_hi:[1,0] neg_lo:[0,1] neg_hi:[0,1]
	s_mov_b32 s18, 0x4a64000
	s_waitcnt lgkmcnt(0)
	v_pk_mul_f32 v[56:57], v[56:57], v[74:75] op_sel_hi:[1,0]
	v_pk_add_f32 v[76:77], v[76:77], v[72:73] op_sel_hi:[1,0] neg_lo:[0,1] neg_hi:[0,1]
	v_pk_fma_f32 v[82:83], v[70:71], v[56:57], v[94:95]
	v_lshlrev_b32_e32 v56, 16, v58
	v_and_b32_e32 v57, 0xffff0000, v58
	v_lshlrev_b32_e32 v58, 16, v59
	v_and_b32_e32 v59, 0xffff0000, v59
	v_pk_add_f32 v[56:57], v[56:57], v[72:73] op_sel_hi:[1,0] neg_lo:[0,1] neg_hi:[0,1]
	v_pk_add_f32 v[58:59], v[58:59], v[72:73] op_sel_hi:[1,0] neg_lo:[0,1] neg_hi:[0,1]
	v_add_co_u32_e32 v72, vcc, s18, v112
	ds_bpermute_b32 v78, v119, v108 offset:20
	s_nop 0
	v_addc_co_u32_e32 v73, vcc, 0, v113, vcc
	s_mov_b32 s18, 0x4a65000
	v_pk_mul_f32 v[76:77], v[76:77], v[74:75] op_sel_hi:[1,0]
	v_add_co_u32_e32 v116, vcc, s18, v112
	v_pk_fma_f32 v[80:81], v[68:69], v[76:77], v[92:93]
	v_pk_mul_f32 v[56:57], v[56:57], v[74:75] op_sel_hi:[1,0]
	v_pk_mul_f32 v[58:59], v[58:59], v[74:75] op_sel_hi:[1,0]
	v_addc_co_u32_e32 v117, vcc, 0, v113, vcc
	v_pk_fma_f32 v[56:57], v[84:85], v[56:57], v[88:89]
	v_pk_fma_f32 v[58:59], v[86:87], v[58:59], v[90:91]
	global_store_dwordx4 v[116:117], v[80:83], off offset:-4096
	global_store_dwordx4 v[72:73], v[56:59], off offset:16
	v_lshlrev_b32_e32 v72, 16, v48
	v_and_b32_e32 v73, 0xffff0000, v48
	v_lshlrev_b32_e32 v48, 16, v49
	v_and_b32_e32 v49, 0xffff0000, v49
	s_waitcnt lgkmcnt(0)
	v_pk_add_f32 v[48:49], v[48:49], v[78:79] op_sel_hi:[1,0] neg_lo:[0,1] neg_hi:[0,1]
	v_pk_add_f32 v[72:73], v[72:73], v[78:79] op_sel_hi:[1,0] neg_lo:[0,1] neg_hi:[0,1]
	v_pk_mul_f32 v[48:49], v[48:49], v[118:119] op_sel_hi:[1,0]
	v_pk_mul_f32 v[72:73], v[72:73], v[118:119] op_sel_hi:[1,0]
	v_pk_fma_f32 v[74:75], v[70:71], v[48:49], v[94:95]
	v_lshlrev_b32_e32 v48, 16, v50
	v_and_b32_e32 v49, 0xffff0000, v50
	v_pk_add_f32 v[48:49], v[48:49], v[78:79] op_sel_hi:[1,0] neg_lo:[0,1] neg_hi:[0,1]
	v_pk_fma_f32 v[72:73], v[68:69], v[72:73], v[92:93]
	v_pk_mul_f32 v[48:49], v[48:49], v[118:119] op_sel_hi:[1,0]
	s_mov_b32 s18, 0x4a66000
	v_pk_fma_f32 v[76:77], v[84:85], v[48:49], v[88:89]
	v_lshlrev_b32_e32 v48, 16, v51
	v_and_b32_e32 v49, 0xffff0000, v51
	v_pk_add_f32 v[48:49], v[48:49], v[78:79] op_sel_hi:[1,0] neg_lo:[0,1] neg_hi:[0,1]
	s_nop 0
	v_pk_mul_f32 v[48:49], v[48:49], v[118:119] op_sel_hi:[1,0]
	ds_bpermute_b32 v118, v119, v109 offset:24
	v_pk_fma_f32 v[78:79], v[86:87], v[48:49], v[90:91]
	global_store_dwordx4 v[116:117], v[72:75], off
	global_store_dwordx4 v[116:117], v[76:79], off offset:16
	ds_bpermute_b32 v116, v119, v108 offset:24
	v_lshlrev_b32_e32 v48, 16, v40
	v_and_b32_e32 v49, 0xffff0000, v40
	v_lshlrev_b32_e32 v40, 16, v41
	v_and_b32_e32 v41, 0xffff0000, v41
	s_waitcnt lgkmcnt(0)
	v_pk_add_f32 v[40:41], v[40:41], v[116:117] op_sel_hi:[1,0] neg_lo:[0,1] neg_hi:[0,1]
	v_pk_add_f32 v[48:49], v[48:49], v[116:117] op_sel_hi:[1,0] neg_lo:[0,1] neg_hi:[0,1]
	v_pk_mul_f32 v[40:41], v[40:41], v[118:119] op_sel_hi:[1,0]
	v_pk_mul_f32 v[48:49], v[48:49], v[118:119] op_sel_hi:[1,0]
	v_pk_fma_f32 v[50:51], v[70:71], v[40:41], v[94:95]
	v_lshlrev_b32_e32 v40, 16, v42
	v_and_b32_e32 v41, 0xffff0000, v42
	v_lshlrev_b32_e32 v42, 16, v43
	v_and_b32_e32 v43, 0xffff0000, v43
	v_pk_add_f32 v[40:41], v[40:41], v[116:117] op_sel_hi:[1,0] neg_lo:[0,1] neg_hi:[0,1]
	v_pk_add_f32 v[42:43], v[42:43], v[116:117] op_sel_hi:[1,0] neg_lo:[0,1] neg_hi:[0,1]
	v_add_co_u32_e32 v116, vcc, s18, v112
	s_mov_b32 s18, 0x4a67000
	s_nop 0
	v_addc_co_u32_e32 v117, vcc, 0, v113, vcc
	v_add_co_u32_e32 v112, vcc, s18, v112
	v_pk_fma_f32 v[48:49], v[68:69], v[48:49], v[92:93]
	v_pk_mul_f32 v[40:41], v[40:41], v[118:119] op_sel_hi:[1,0]
	v_pk_mul_f32 v[42:43], v[42:43], v[118:119] op_sel_hi:[1,0]
	v_addc_co_u32_e32 v113, vcc, 0, v113, vcc
	ds_bpermute_b32 v108, v119, v108 offset:28
	v_pk_fma_f32 v[40:41], v[84:85], v[40:41], v[88:89]
	v_pk_fma_f32 v[42:43], v[86:87], v[42:43], v[90:91]
	global_store_dwordx4 v[112:113], v[48:51], off offset:-4096
	global_store_dwordx4 v[116:117], v[40:43], off offset:16
	ds_bpermute_b32 v116, v119, v109 offset:28
	v_lshlrev_b32_e32 v118, 16, v32
	v_and_b32_e32 v119, 0xffff0000, v32
	v_lshlrev_b32_e32 v32, 16, v33
	v_and_b32_e32 v33, 0xffff0000, v33
	s_waitcnt lgkmcnt(1)
	v_pk_add_f32 v[32:33], v[32:33], v[108:109] op_sel_hi:[1,0] neg_lo:[0,1] neg_hi:[0,1]
	v_pk_add_f32 v[118:119], v[118:119], v[108:109] op_sel_hi:[1,0] neg_lo:[0,1] neg_hi:[0,1]
	s_waitcnt lgkmcnt(0)
	v_pk_mul_f32 v[32:33], v[32:33], v[116:117] op_sel_hi:[1,0]
	v_pk_mul_f32 v[118:119], v[118:119], v[116:117] op_sel_hi:[1,0]
	v_pk_fma_f32 v[70:71], v[70:71], v[32:33], v[94:95]
	v_lshlrev_b32_e32 v32, 16, v34
	v_and_b32_e32 v33, 0xffff0000, v34
	v_pk_add_f32 v[32:33], v[32:33], v[108:109] op_sel_hi:[1,0] neg_lo:[0,1] neg_hi:[0,1]
	v_lshlrev_b32_e32 v34, 16, v35
	v_and_b32_e32 v35, 0xffff0000, v35
	v_pk_mul_f32 v[32:33], v[32:33], v[116:117] op_sel_hi:[1,0]
	v_pk_add_f32 v[34:35], v[34:35], v[108:109] op_sel_hi:[1,0] neg_lo:[0,1] neg_hi:[0,1]
	v_pk_fma_f32 v[32:33], v[84:85], v[32:33], v[88:89]
	v_pk_mul_f32 v[34:35], v[34:35], v[116:117] op_sel_hi:[1,0]
	v_and_b32_e32 v84, 0x780, v184
	v_pk_fma_f32 v[68:69], v[68:69], v[118:119], v[92:93]
	v_pk_fma_f32 v[34:35], v[86:87], v[34:35], v[90:91]
	v_or_b32_e32 v86, s8, v84
	v_mov_b32_e32 v87, s9
	global_store_dwordx4 v[112:113], v[68:71], off
	global_store_dwordx4 v[112:113], v[32:35], off offset:16
	v_lshlrev_b64 v[84:85], 9, v[86:87]
	v_lshl_add_u64 v[86:87], v[86:87], 2, v[110:111]
	v_lshl_add_u64 v[84:85], s[76:77], 0, v[84:85]
	global_load_dword v88, v[86:87], off
	global_load_dword v89, v[84:85], off
	global_load_dword v146, v[86:87], off offset:4
	global_load_dwordx2 v[148:149], v[84:85], off offset:512
	global_load_dword v150, v[86:87], off offset:8
	global_load_dwordx3 v[152:154], v[84:85], off offset:1024
	global_load_dword v155, v[86:87], off offset:12
	global_load_dwordx4 v[156:159], v[84:85], off offset:1536
	global_load_dword v160, v[86:87], off offset:16
	global_load_dwordx4 v[162:165], v[84:85], off offset:2048
	global_load_dword v166, v[84:85], off offset:2064
	global_load_dword v167, v[86:87], off offset:20
	global_load_dwordx2 v[168:169], v[84:85], off offset:2576
	global_load_dwordx4 v[170:173], v[84:85], off offset:2560
	global_load_dword v174, v[86:87], off offset:24
	global_load_dwordx4 v[176:179], v[84:85], off offset:3072
	global_load_dwordx3 v[180:182], v[84:85], off offset:3088
	global_load_dword v183, v[86:87], off offset:28
	global_load_dwordx4 v[186:189], v[84:85], off offset:3600
	global_load_dwordx4 v[190:193], v[84:85], off offset:3584
	v_lshlrev_b32_e32 v109, 16, v29
	v_and_b32_e32 v29, 0xffff0000, v29
	v_lshlrev_b32_e32 v110, 16, v30
	v_and_b32_e32 v30, 0xffff0000, v30
	v_lshlrev_b32_e32 v111, 16, v31
	v_and_b32_e32 v31, 0xffff0000, v31
	s_waitcnt vmcnt(0)
	v_fma_f32 v90, v55, v89, v88
	v_fma_f32 v91, v44, v89, v88
	v_fma_f32 v92, v45, v89, v88
	v_fma_f32 v93, v46, v89, v88
	v_fma_f32 v94, v47, v89, v88
	v_fma_f32 v95, v52, v89, v88
	v_fma_f32 v108, v53, v89, v88
	v_fmac_f32_e32 v88, v54, v89
	v_lshlrev_b32_e32 v89, 16, v28
	v_and_b32_e32 v28, 0xffff0000, v28
	v_mul_f32_e32 v89, v91, v89
	v_mul_f32_e32 v28, v92, v28
	v_mul_f32_e32 v29, v94, v29
	v_mul_f32_e32 v91, v93, v109
	v_mul_f32_e32 v30, v108, v30
	v_mul_f32_e32 v93, v88, v111
	v_mul_f32_e32 v31, v90, v31
	v_cvt_pk_bf16_f32 v88, v89, v28
	v_cvt_pk_bf16_f32 v89, v91, v29
	v_mov_b64_e32 v[28:29], s[12:13]
	v_mul_f32_e32 v92, v95, v110
	v_cvt_pk_bf16_f32 v90, v92, v30
	v_cvt_pk_bf16_f32 v91, v93, v31
	v_mad_i64_i32 v[30:31], s[18:19], v115, s68, v[28:29]
	v_lshl_add_u64 v[30:31], v[30:31], 0, v[184:185]
	global_store_dwordx4 v[30:31], v[88:91], off offset:2048
	s_nop 1
	v_mov_b32_e32 v115, v146
	v_mov_b32_e32 v116, v148
	v_mov_b32_e32 v117, v149
	v_mov_b32_e32 v30, v55
	v_mov_b32_e32 v31, v63
	v_pk_mul_f32 v[88:89], v[30:31], v[116:117]
	s_nop 0
	v_add_f32_e32 v88, v115, v88
	v_add_f32_e32 v118, v88, v89
	v_mov_b32_e32 v88, v44
	v_mov_b32_e32 v89, v104
	v_pk_mul_f32 v[90:91], v[88:89], v[116:117]
	v_mul_f32_e32 v27, v118, v27
	v_add_f32_e32 v90, v115, v90
	v_add_f32_e32 v119, v90, v91
	v_mov_b32_e32 v90, v45
	v_mov_b32_e32 v91, v105
	v_pk_mul_f32 v[92:93], v[90:91], v[116:117]
	s_nop 0
	v_add_f32_e32 v92, v115, v92
	v_add_f32_e32 v120, v92, v93
	v_mov_b32_e32 v92, v46
	v_mov_b32_e32 v93, v106
	v_pk_mul_f32 v[94:95], v[92:93], v[116:117]
	s_nop 0
	v_add_f32_e32 v94, v115, v94
	v_add_f32_e32 v121, v94, v95
	v_mov_b32_e32 v94, v47
	v_mov_b32_e32 v95, v107
	v_pk_mul_f32 v[108:109], v[94:95], v[116:117]
	s_nop 0
	v_add_f32_e32 v108, v115, v108
	v_add_f32_e32 v122, v108, v109
	v_mov_b32_e32 v108, v52
	v_mov_b32_e32 v109, v60
	v_pk_mul_f32 v[110:111], v[108:109], v[116:117]
	s_nop 0
	v_add_f32_e32 v110, v115, v110
	v_add_f32_e32 v123, v110, v111
	v_mov_b32_e32 v110, v53
	v_mov_b32_e32 v111, v61
	v_pk_mul_f32 v[112:113], v[110:111], v[116:117]
	s_nop 0
	v_add_f32_e32 v112, v115, v112
	v_add_f32_e32 v126, v112, v113
	v_mov_b32_e32 v112, v54
	v_mov_b32_e32 v113, v62
	v_pk_mul_f32 v[116:117], v[112:113], v[116:117]
	v_mul_f32_e32 v26, v126, v26
	v_add_f32_e32 v115, v115, v116
	v_add_f32_e32 v115, v115, v117
	v_lshlrev_b32_e32 v116, 16, v24
	v_and_b32_e32 v24, 0xffff0000, v24
	v_lshlrev_b32_e32 v117, 16, v25
	v_and_b32_e32 v25, 0xffff0000, v25
	v_mul_f32_e32 v24, v120, v24
	v_mul_f32_e32 v25, v122, v25
	v_mul_f32_e32 v115, v115, v132
	v_mul_f32_e32 v116, v119, v116
	v_mul_f32_e32 v117, v121, v117
	v_mul_f32_e32 v119, v123, v127
	v_cvt_pk_bf16_f32 v24, v116, v24
	v_cvt_pk_bf16_f32 v25, v117, v25
	v_cvt_pk_bf16_f32 v26, v119, v26
	v_cvt_pk_bf16_f32 v27, v115, v27
	v_mad_i64_i32 v[114:115], s[18:19], v114, s68, v[28:29]
	v_lshl_add_u64 v[114:115], v[114:115], 0, v[184:185]
	global_store_dwordx4 v[114:115], v[24:27], off offset:2048
	s_nop 1
	v_mov_b32_e32 v27, v150
	s_nop 0
	s_nop 1
	v_mov_b32_e32 v24, v152
	v_mov_b32_e32 v25, v153
	v_mov_b32_e32 v26, v154
	v_mov_b32_e32 v114, v63
	v_mov_b32_e32 v115, v39
	v_mov_b32_e32 v116, v104
	v_mov_b32_e32 v117, v100
	v_mov_b32_e32 v104, v105
	v_mov_b32_e32 v105, v101
	v_mov_b32_e32 v123, v37
	v_mov_b32_e32 v63, v38
	v_mov_b32_e32 v126, v25
	v_mov_b32_e32 v127, v26
	v_fma_f32 v26, v55, v24, v27
	v_fma_f32 v118, v44, v24, v27
	v_fma_f32 v119, v45, v24, v27
	v_fma_f32 v120, v46, v24, v27
	v_fma_f32 v121, v47, v24, v27
	v_fma_f32 v122, v52, v24, v27
	v_fma_f32 v132, v53, v24, v27
	v_fmac_f32_e32 v27, v54, v24
	v_pk_mul_f32 v[24:25], v[114:115], v[126:127]
	s_nop 0
	v_add_f32_e32 v24, v26, v24
	v_add_f32_e32 v26, v24, v25
	v_pk_mul_f32 v[24:25], v[116:117], v[126:127]
	s_nop 0
	v_add_f32_e32 v24, v118, v24
	v_add_f32_e32 v133, v24, v25
	v_pk_mul_f32 v[24:25], v[104:105], v[126:127]
	v_mov_b32_e32 v118, v106
	v_add_f32_e32 v24, v119, v24
	v_mov_b32_e32 v119, v102
	v_add_f32_e32 v134, v24, v25
	v_pk_mul_f32 v[24:25], v[118:119], v[126:127]
	v_mov_b32_e32 v106, v107
	v_add_f32_e32 v24, v120, v24
	v_mov_b32_e32 v107, v103
	v_add_f32_e32 v135, v24, v25
	v_pk_mul_f32 v[24:25], v[106:107], v[126:127]
	v_mov_b32_e32 v120, v60
	v_add_f32_e32 v24, v121, v24
	v_mov_b32_e32 v121, v36
	v_add_f32_e32 v136, v24, v25
	v_pk_mul_f32 v[24:25], v[120:121], v[126:127]
	s_nop 0
	v_add_f32_e32 v24, v122, v24
	v_mov_b32_e32 v122, v61
	v_add_f32_e32 v60, v24, v25
	v_pk_mul_f32 v[24:25], v[122:123], v[126:127]
	s_nop 0
	v_add_f32_e32 v24, v132, v24
	v_add_f32_e32 v61, v24, v25
	v_pk_mul_f32 v[24:25], v[62:63], v[126:127]
	v_lshlrev_b32_e32 v126, 16, v22
	v_add_f32_e32 v24, v27, v24
	v_add_f32_e32 v24, v24, v25
	v_lshlrev_b32_e32 v25, 16, v20
	v_and_b32_e32 v20, 0xffff0000, v20
	v_lshlrev_b32_e32 v27, 16, v21
	v_and_b32_e32 v21, 0xffff0000, v21
	v_and_b32_e32 v22, 0xffff0000, v22
	v_lshlrev_b32_e32 v127, 16, v23
	v_and_b32_e32 v23, 0xffff0000, v23
	v_mul_f32_e32 v25, v133, v25
	v_mul_f32_e32 v20, v134, v20
	v_mul_f32_e32 v21, v136, v21
	v_mul_f32_e32 v22, v61, v22
	v_mul_f32_e32 v24, v24, v127
	v_mul_f32_e32 v23, v26, v23
	v_mul_f32_e32 v27, v135, v27
	v_mul_f32_e32 v60, v60, v126
	v_cvt_pk_bf16_f32 v20, v25, v20
	v_cvt_pk_bf16_f32 v21, v27, v21
	v_cvt_pk_bf16_f32 v22, v60, v22
	v_cvt_pk_bf16_f32 v23, v24, v23
	v_mad_i64_i32 v[24:25], s[18:19], v125, s68, v[28:29]
	v_lshl_add_u64 v[24:25], v[24:25], 0, v[184:185]
	global_store_dwordx4 v[24:25], v[20:23], off offset:2048
	s_nop 1
	v_mov_b32_e32 v22, v155
	s_nop 0
	s_nop 1
	v_mov_b32_e32 v132, v156
	v_mov_b32_e32 v133, v157
	v_mov_b32_e32 v134, v158
	v_mov_b32_e32 v135, v159
	v_pk_mul_f32 v[20:21], v[30:31], v[132:133]
	s_nop 0
	v_add_f32_e32 v20, v22, v20
	v_add_f32_e32 v24, v20, v21
	v_pk_mul_f32 v[20:21], v[88:89], v[132:133]
	s_nop 0
	v_add_f32_e32 v20, v22, v20
	v_add_f32_e32 v26, v20, v21
	v_pk_mul_f32 v[20:21], v[90:91], v[132:133]
	s_nop 0
	v_add_f32_e32 v20, v22, v20
	v_add_f32_e32 v60, v20, v21
	v_pk_mul_f32 v[20:21], v[92:93], v[132:133]
	s_nop 0
	v_add_f32_e32 v20, v22, v20
	v_add_f32_e32 v125, v20, v21
	v_pk_mul_f32 v[20:21], v[94:95], v[132:133]
	s_nop 0
	v_add_f32_e32 v20, v22, v20
	v_add_f32_e32 v126, v20, v21
	v_pk_mul_f32 v[20:21], v[108:109], v[132:133]
	s_nop 0
	v_add_f32_e32 v20, v22, v20
	v_add_f32_e32 v127, v20, v21
	v_pk_mul_f32 v[20:21], v[110:111], v[132:133]
	s_nop 0
	v_add_f32_e32 v20, v22, v20
	v_add_f32_e32 v136, v20, v21
	v_pk_mul_f32 v[20:21], v[112:113], v[132:133]
	s_nop 0
	v_add_f32_e32 v20, v22, v20
	v_add_f32_e32 v132, v20, v21
	v_mov_b32_e32 v20, v39
	v_mov_b32_e32 v21, v67
	v_pk_mul_f32 v[22:23], v[20:21], v[134:135]
	s_nop 0
	v_add_f32_e32 v22, v24, v22
	v_add_f32_e32 v133, v22, v23
	v_mov_b32_e32 v22, v100
	v_mov_b32_e32 v23, v96
	v_pk_mul_f32 v[24:25], v[22:23], v[134:135]
	s_nop 0
	v_add_f32_e32 v24, v26, v24
	v_add_f32_e32 v137, v24, v25
	v_mov_b32_e32 v24, v101
	v_mov_b32_e32 v25, v97
	v_pk_mul_f32 v[26:27], v[24:25], v[134:135]
	s_nop 0
	v_add_f32_e32 v26, v60, v26
	v_add_f32_e32 v138, v26, v27
	v_mov_b32_e32 v26, v102
	v_mov_b32_e32 v27, v98
	v_pk_mul_f32 v[60:61], v[26:27], v[134:135]
	s_nop 0
	v_add_f32_e32 v39, v125, v60
	v_add_f32_e32 v125, v39, v61
	v_mov_b32_e32 v60, v103
	v_mov_b32_e32 v61, v99
	v_pk_mul_f32 v[100:101], v[60:61], v[134:135]
	s_nop 0
	v_add_f32_e32 v39, v126, v100
	v_add_f32_e32 v126, v39, v101
	v_mov_b32_e32 v100, v36
	v_mov_b32_e32 v101, v64
	v_pk_mul_f32 v[102:103], v[100:101], v[134:135]
	s_nop 0
	v_add_f32_e32 v36, v127, v102
	v_add_f32_e32 v127, v36, v103
	v_mov_b32_e32 v36, v37
	v_mov_b32_e32 v37, v65
	v_pk_mul_f32 v[102:103], v[36:37], v[134:135]
	s_nop 0
	v_add_f32_e32 v39, v136, v102
	v_add_f32_e32 v136, v39, v103
	v_mov_b32_e32 v39, v66
	v_pk_mul_f32 v[102:103], v[38:39], v[134:135]
	v_lshlrev_b32_e32 v134, 16, v18
	v_add_f32_e32 v102, v132, v102
	v_add_f32_e32 v102, v102, v103
	v_lshlrev_b32_e32 v103, 16, v16
	v_and_b32_e32 v16, 0xffff0000, v16
	v_lshlrev_b32_e32 v132, 16, v17
	v_and_b32_e32 v17, 0xffff0000, v17
	v_and_b32_e32 v18, 0xffff0000, v18
	v_lshlrev_b32_e32 v135, 16, v19
	v_and_b32_e32 v19, 0xffff0000, v19
	v_mul_f32_e32 v103, v137, v103
	v_mul_f32_e32 v16, v138, v16
	v_mul_f32_e32 v17, v126, v17
	v_mul_f32_e32 v18, v136, v18
	v_mul_f32_e32 v102, v102, v135
	v_mul_f32_e32 v19, v133, v19
	v_mul_f32_e32 v125, v125, v132
	v_mul_f32_e32 v126, v127, v134
	v_cvt_pk_bf16_f32 v16, v103, v16
	v_cvt_pk_bf16_f32 v17, v125, v17
	v_cvt_pk_bf16_f32 v18, v126, v18
	v_cvt_pk_bf16_f32 v19, v102, v19
	v_mad_i64_i32 v[102:103], s[18:19], v124, s68, v[28:29]
	v_lshl_add_u64 v[102:103], v[102:103], 0, v[184:185]
	global_store_dwordx4 v[102:103], v[16:19], off offset:2048
	s_nop 1
	v_mov_b32_e32 v124, v160
	s_nop 0
	s_nop 1
	v_mov_b32_e32 v16, v162
	v_mov_b32_e32 v17, v163
	v_mov_b32_e32 v18, v164
	v_mov_b32_e32 v19, v165
	v_mov_b32_e32 v133, v166
	v_mov_b32_e32 v102, v17
	v_mov_b32_e32 v103, v18
	v_mov_b32_e32 v132, v19
	v_fma_f32 v18, v55, v16, v124
	v_fma_f32 v19, v44, v16, v124
	v_fma_f32 v125, v45, v16, v124
	v_fma_f32 v126, v46, v16, v124
	v_fma_f32 v127, v47, v16, v124
	v_fma_f32 v134, v52, v16, v124
	v_fma_f32 v135, v53, v16, v124
	v_fmac_f32_e32 v124, v54, v16
	v_pk_mul_f32 v[16:17], v[114:115], v[102:103]
	s_nop 0
	v_add_f32_e32 v16, v18, v16
	v_add_f32_e32 v18, v16, v17
	v_pk_mul_f32 v[16:17], v[116:117], v[102:103]
	s_nop 0
	v_add_f32_e32 v16, v19, v16
	v_add_f32_e32 v19, v16, v17
	v_pk_mul_f32 v[16:17], v[104:105], v[102:103]
	s_nop 0
	v_add_f32_e32 v16, v125, v16
	v_add_f32_e32 v136, v16, v17
	v_pk_mul_f32 v[16:17], v[118:119], v[102:103]
	v_mov_b32_e32 v125, v80
	v_add_f32_e32 v16, v126, v16
	v_add_f32_e32 v137, v16, v17
	v_pk_mul_f32 v[16:17], v[106:107], v[102:103]
	v_mov_b32_e32 v126, v98
	v_add_f32_e32 v16, v127, v16
	v_add_f32_e32 v138, v16, v17
	v_pk_mul_f32 v[16:17], v[120:121], v[102:103]
	v_mov_b32_e32 v127, v82
	v_add_f32_e32 v16, v134, v16
	v_add_f32_e32 v139, v16, v17
	v_pk_mul_f32 v[16:17], v[122:123], v[102:103]
	v_mov_b32_e32 v98, v99
	v_add_f32_e32 v16, v135, v16
	v_add_f32_e32 v140, v16, v17
	v_pk_mul_f32 v[16:17], v[62:63], v[102:103]
	v_mov_b32_e32 v102, v67
	v_add_f32_e32 v16, v124, v16
	v_mov_b32_e32 v103, v59
	v_add_f32_e32 v141, v16, v17
	v_pk_mul_f32 v[16:17], v[102:103], v[132:133]
	v_mov_b32_e32 v124, v96
	v_add_f32_e32 v16, v18, v16
	v_add_f32_e32 v18, v16, v17
	v_pk_mul_f32 v[16:17], v[124:125], v[132:133]
	v_mov_b32_e32 v96, v97
	v_add_f32_e32 v16, v19, v16
	v_mov_b32_e32 v97, v81
	v_add_f32_e32 v19, v16, v17
	v_pk_mul_f32 v[16:17], v[96:97], v[132:133]
	v_mov_b32_e32 v99, v83
	v_add_f32_e32 v16, v136, v16
	v_add_f32_e32 v142, v16, v17
	v_pk_mul_f32 v[16:17], v[126:127], v[132:133]
	v_mov_b32_e32 v134, v64
	v_add_f32_e32 v16, v137, v16
	v_add_f32_e32 v143, v16, v17
	v_pk_mul_f32 v[16:17], v[98:99], v[132:133]
	v_mov_b32_e32 v135, v56
	v_add_f32_e32 v16, v138, v16
	v_add_f32_e32 v138, v16, v17
	v_pk_mul_f32 v[16:17], v[134:135], v[132:133]
	v_mov_b32_e32 v136, v65
	v_add_f32_e32 v16, v139, v16
	v_mov_b32_e32 v137, v57
	v_add_f32_e32 v64, v16, v17
	v_pk_mul_f32 v[16:17], v[136:137], v[132:133]
	v_mov_b32_e32 v67, v58
	v_add_f32_e32 v16, v140, v16
	v_add_f32_e32 v65, v16, v17
	v_pk_mul_f32 v[16:17], v[66:67], v[132:133]
	v_lshlrev_b32_e32 v132, 16, v13
	v_add_f32_e32 v16, v141, v16
	v_add_f32_e32 v16, v16, v17
	v_lshlrev_b32_e32 v17, 16, v12
	v_and_b32_e32 v12, 0xffff0000, v12
	v_and_b32_e32 v13, 0xffff0000, v13
	v_lshlrev_b32_e32 v133, 16, v14
	v_and_b32_e32 v14, 0xffff0000, v14
	v_lshlrev_b32_e32 v139, 16, v15
	v_and_b32_e32 v15, 0xffff0000, v15
	v_mul_f32_e32 v17, v19, v17
	v_mul_f32_e32 v12, v142, v12
	v_mul_f32_e32 v13, v138, v13
	v_mul_f32_e32 v14, v65, v14
	v_mul_f32_e32 v16, v16, v139
	v_mul_f32_e32 v15, v18, v15
	v_mul_f32_e32 v19, v143, v132
	v_mul_f32_e32 v64, v64, v133
	v_cvt_pk_bf16_f32 v12, v17, v12
	v_cvt_pk_bf16_f32 v13, v19, v13
	v_cvt_pk_bf16_f32 v14, v64, v14
	v_cvt_pk_bf16_f32 v15, v16, v15
	v_mad_i64_i32 v[16:17], s[18:19], v131, s68, v[28:29]
	v_lshl_add_u64 v[16:17], v[16:17], 0, v[184:185]
	global_store_dwordx4 v[16:17], v[12:15], off offset:2048
	s_nop 1
	v_mov_b32_e32 v18, v167
	v_mov_b32_e32 v132, v168
	v_mov_b32_e32 v133, v169
	s_nop 0
	s_nop 1
	v_mov_b32_e32 v12, v170
	v_mov_b32_e32 v13, v171
	v_mov_b32_e32 v14, v172
	v_mov_b32_e32 v15, v173
	v_pk_mul_f32 v[16:17], v[30:31], v[12:13]
	s_nop 0
	v_add_f32_e32 v16, v18, v16
	v_add_f32_e32 v19, v16, v17
	v_pk_mul_f32 v[16:17], v[88:89], v[12:13]
	s_nop 0
	v_add_f32_e32 v16, v18, v16
	v_add_f32_e32 v64, v16, v17
	v_pk_mul_f32 v[16:17], v[90:91], v[12:13]
	s_nop 0
	v_add_f32_e32 v16, v18, v16
	v_add_f32_e32 v65, v16, v17
	v_pk_mul_f32 v[16:17], v[92:93], v[12:13]
	s_nop 0
	v_add_f32_e32 v16, v18, v16
	v_add_f32_e32 v131, v16, v17
	v_pk_mul_f32 v[16:17], v[94:95], v[12:13]
	s_nop 0
	v_add_f32_e32 v16, v18, v16
	v_add_f32_e32 v138, v16, v17
	v_pk_mul_f32 v[16:17], v[108:109], v[12:13]
	s_nop 0
	v_add_f32_e32 v16, v18, v16
	v_add_f32_e32 v139, v16, v17
	v_pk_mul_f32 v[16:17], v[110:111], v[12:13]
	v_pk_mul_f32 v[12:13], v[112:113], v[12:13]
	v_add_f32_e32 v16, v18, v16
	v_add_f32_e32 v12, v18, v12
	v_add_f32_e32 v16, v16, v17
	v_add_f32_e32 v17, v12, v13
	v_pk_mul_f32 v[12:13], v[20:21], v[14:15]
	s_nop 0
	v_add_f32_e32 v12, v19, v12
	v_add_f32_e32 v18, v12, v13
	v_pk_mul_f32 v[12:13], v[22:23], v[14:15]
	s_nop 0
	v_add_f32_e32 v12, v64, v12
	v_add_f32_e32 v19, v12, v13
	v_pk_mul_f32 v[12:13], v[24:25], v[14:15]
	s_nop 0
	v_add_f32_e32 v12, v65, v12
	v_add_f32_e32 v64, v12, v13
	v_pk_mul_f32 v[12:13], v[26:27], v[14:15]
	s_nop 0
	v_add_f32_e32 v12, v131, v12
	v_add_f32_e32 v131, v12, v13
	v_pk_mul_f32 v[12:13], v[60:61], v[14:15]
	s_nop 0
	v_add_f32_e32 v12, v138, v12
	v_add_f32_e32 v138, v12, v13
	v_pk_mul_f32 v[12:13], v[100:101], v[14:15]
	s_nop 0
	v_add_f32_e32 v12, v139, v12
	v_add_f32_e32 v139, v12, v13
	v_pk_mul_f32 v[12:13], v[36:37], v[14:15]
	s_nop 0
	v_add_f32_e32 v12, v16, v12
	v_add_f32_e32 v140, v12, v13
	v_pk_mul_f32 v[12:13], v[38:39], v[14:15]
	s_nop 0
	v_add_f32_e32 v12, v17, v12
	v_add_f32_e32 v141, v12, v13
	v_mov_b32_e32 v12, v59
	v_mov_b32_e32 v13, v79
	v_pk_mul_f32 v[14:15], v[12:13], v[132:133]
	s_nop 0
	v_add_f32_e32 v14, v18, v14
	v_add_f32_e32 v142, v14, v15
	v_mov_b32_e32 v14, v80
	v_mov_b32_e32 v15, v72
	v_pk_mul_f32 v[16:17], v[14:15], v[132:133]
	s_nop 0
	v_add_f32_e32 v16, v19, v16
	v_add_f32_e32 v143, v16, v17
	v_mov_b32_e32 v16, v81
	v_mov_b32_e32 v17, v73
	v_pk_mul_f32 v[18:19], v[16:17], v[132:133]
	s_nop 0
	v_add_f32_e32 v18, v64, v18
	v_add_f32_e32 v144, v18, v19
	v_mov_b32_e32 v18, v82
	v_mov_b32_e32 v19, v74
	v_pk_mul_f32 v[64:65], v[18:19], v[132:133]
	s_nop 0
	v_add_f32_e32 v59, v131, v64
	v_add_f32_e32 v131, v59, v65
	v_mov_b32_e32 v64, v83
	v_mov_b32_e32 v65, v75
	v_pk_mul_f32 v[80:81], v[64:65], v[132:133]
	s_nop 0
	v_add_f32_e32 v59, v138, v80
	v_add_f32_e32 v138, v59, v81
	v_mov_b32_e32 v80, v56
	v_mov_b32_e32 v81, v76
	v_pk_mul_f32 v[82:83], v[80:81], v[132:133]
	s_nop 0
	v_add_f32_e32 v56, v139, v82
	v_add_f32_e32 v139, v56, v83
	v_mov_b32_e32 v56, v57
	v_mov_b32_e32 v57, v77
	v_pk_mul_f32 v[82:83], v[56:57], v[132:133]
	s_nop 0
	v_add_f32_e32 v59, v140, v82
	v_add_f32_e32 v140, v59, v83
	v_mov_b32_e32 v59, v78
	v_pk_mul_f32 v[82:83], v[58:59], v[132:133]
	v_lshlrev_b32_e32 v132, 16, v9
	v_add_f32_e32 v82, v141, v82
	v_add_f32_e32 v82, v82, v83
	v_lshlrev_b32_e32 v83, 16, v8
	v_and_b32_e32 v8, 0xffff0000, v8
	v_and_b32_e32 v9, 0xffff0000, v9
	v_lshlrev_b32_e32 v133, 16, v10
	v_and_b32_e32 v10, 0xffff0000, v10
	v_lshlrev_b32_e32 v141, 16, v11
	v_and_b32_e32 v11, 0xffff0000, v11
	v_mul_f32_e32 v83, v143, v83
	v_mul_f32_e32 v8, v144, v8
	v_mul_f32_e32 v9, v138, v9
	v_mul_f32_e32 v10, v140, v10
	v_mul_f32_e32 v82, v82, v141
	v_mul_f32_e32 v11, v142, v11
	v_mul_f32_e32 v131, v131, v132
	v_mul_f32_e32 v132, v139, v133
	v_cvt_pk_bf16_f32 v8, v83, v8
	v_cvt_pk_bf16_f32 v9, v131, v9
	v_cvt_pk_bf16_f32 v10, v132, v10
	v_cvt_pk_bf16_f32 v11, v82, v11
	v_mad_i64_i32 v[82:83], s[18:19], v130, s68, v[28:29]
	v_lshl_add_u64 v[82:83], v[82:83], 0, v[184:185]
	global_store_dwordx4 v[82:83], v[8:11], off offset:2048
	s_nop 1
	v_mov_b32_e32 v133, v174
	s_nop 0
	s_nop 1
	v_mov_b32_e32 v8, v176
	v_mov_b32_e32 v9, v177
	v_mov_b32_e32 v10, v178
	v_mov_b32_e32 v11, v179
	v_mov_b32_e32 v130, v180
	v_mov_b32_e32 v131, v181
	v_mov_b32_e32 v132, v182
	v_mov_b32_e32 v82, v9
	v_mov_b32_e32 v83, v10
	v_fma_f32 v55, v55, v8, v133
	v_fma_f32 v44, v44, v8, v133
	v_fma_f32 v45, v45, v8, v133
	v_fma_f32 v46, v46, v8, v133
	v_fma_f32 v47, v47, v8, v133
	v_fma_f32 v52, v52, v8, v133
	v_fma_f32 v53, v53, v8, v133
	v_fmac_f32_e32 v133, v54, v8
	v_pk_mul_f32 v[8:9], v[114:115], v[82:83]
	v_mov_b32_e32 v10, v11
	v_add_f32_e32 v8, v55, v8
	v_add_f32_e32 v54, v8, v9
	v_pk_mul_f32 v[8:9], v[116:117], v[82:83]
	v_mov_b32_e32 v11, v130
	v_add_f32_e32 v8, v44, v8
	v_add_f32_e32 v44, v8, v9
	v_pk_mul_f32 v[8:9], v[104:105], v[82:83]
	v_mov_b32_e32 v130, v131
	v_add_f32_e32 v8, v45, v8
	v_add_f32_e32 v45, v8, v9
	v_pk_mul_f32 v[8:9], v[118:119], v[82:83]
	v_mov_b32_e32 v131, v132
	v_add_f32_e32 v8, v46, v8
	v_add_f32_e32 v46, v8, v9
	v_pk_mul_f32 v[8:9], v[106:107], v[82:83]
	s_nop 0
	v_add_f32_e32 v8, v47, v8
	v_add_f32_e32 v47, v8, v9
	v_pk_mul_f32 v[8:9], v[120:121], v[82:83]
	s_nop 0
	v_add_f32_e32 v8, v52, v8
	v_add_f32_e32 v52, v8, v9
	v_pk_mul_f32 v[8:9], v[122:123], v[82:83]
	s_nop 0
	v_add_f32_e32 v8, v53, v8
	v_add_f32_e32 v53, v8, v9
	v_pk_mul_f32 v[8:9], v[62:63], v[82:83]
	s_nop 0
	v_add_f32_e32 v8, v133, v8
	v_add_f32_e32 v55, v8, v9
	v_pk_mul_f32 v[8:9], v[102:103], v[10:11]
	s_nop 0
	v_add_f32_e32 v8, v54, v8
	v_add_f32_e32 v54, v8, v9
	v_pk_mul_f32 v[8:9], v[124:125], v[10:11]
	s_nop 0
	v_add_f32_e32 v8, v44, v8
	v_add_f32_e32 v44, v8, v9
	v_pk_mul_f32 v[8:9], v[96:97], v[10:11]
	s_nop 0
	v_add_f32_e32 v8, v45, v8
	v_add_f32_e32 v45, v8, v9
	v_pk_mul_f32 v[8:9], v[126:127], v[10:11]
	s_nop 0
	v_add_f32_e32 v8, v46, v8
	v_add_f32_e32 v46, v8, v9
	v_pk_mul_f32 v[8:9], v[98:99], v[10:11]
	s_nop 0
	v_add_f32_e32 v8, v47, v8
	v_add_f32_e32 v47, v8, v9
	v_pk_mul_f32 v[8:9], v[134:135], v[10:11]
	s_nop 0
	v_add_f32_e32 v8, v52, v8
	v_add_f32_e32 v52, v8, v9
	v_pk_mul_f32 v[8:9], v[136:137], v[10:11]
	s_nop 0
	v_add_f32_e32 v8, v53, v8
	v_add_f32_e32 v53, v8, v9
	v_pk_mul_f32 v[8:9], v[66:67], v[10:11]
	s_nop 0
	v_add_f32_e32 v8, v55, v8
	v_add_f32_e32 v10, v8, v9
	v_mov_b32_e32 v8, v79
	v_mov_b32_e32 v9, v43
	v_pk_mul_f32 v[8:9], v[8:9], v[130:131]
	v_mov_b32_e32 v79, v42
	v_add_f32_e32 v8, v54, v8
	v_add_f32_e32 v11, v8, v9
	v_mov_b32_e32 v8, v72
	v_mov_b32_e32 v9, v48
	v_pk_mul_f32 v[8:9], v[8:9], v[130:131]
	v_lshlrev_b32_e32 v54, 16, v6
	v_add_f32_e32 v8, v44, v8
	v_add_f32_e32 v44, v8, v9
	v_mov_b32_e32 v8, v73
	v_mov_b32_e32 v9, v49
	v_pk_mul_f32 v[8:9], v[8:9], v[130:131]
	v_and_b32_e32 v6, 0xffff0000, v6
	v_add_f32_e32 v8, v45, v8
	v_add_f32_e32 v45, v8, v9
	v_mov_b32_e32 v8, v74
	v_mov_b32_e32 v9, v50
	v_pk_mul_f32 v[8:9], v[8:9], v[130:131]
	v_lshlrev_b32_e32 v55, 16, v7
	v_add_f32_e32 v8, v46, v8
	v_add_f32_e32 v46, v8, v9
	v_mov_b32_e32 v8, v75
	v_mov_b32_e32 v9, v51
	v_pk_mul_f32 v[8:9], v[8:9], v[130:131]
	v_and_b32_e32 v7, 0xffff0000, v7
	v_add_f32_e32 v8, v47, v8
	v_add_f32_e32 v47, v8, v9
	v_mov_b32_e32 v8, v76
	v_mov_b32_e32 v9, v40
	v_pk_mul_f32 v[8:9], v[8:9], v[130:131]
	v_mul_f32_e32 v7, v11, v7
	v_add_f32_e32 v8, v52, v8
	v_add_f32_e32 v52, v8, v9
	v_mov_b32_e32 v8, v77
	v_mov_b32_e32 v9, v41
	v_pk_mul_f32 v[8:9], v[8:9], v[130:131]
	s_nop 0
	v_add_f32_e32 v8, v53, v8
	v_add_f32_e32 v53, v8, v9
	v_pk_mul_f32 v[8:9], v[78:79], v[130:131]
	v_mul_f32_e32 v6, v53, v6
	v_add_f32_e32 v8, v10, v8
	v_add_f32_e32 v8, v8, v9
	v_lshlrev_b32_e32 v9, 16, v4
	v_and_b32_e32 v4, 0xffff0000, v4
	v_lshlrev_b32_e32 v10, 16, v5
	v_and_b32_e32 v5, 0xffff0000, v5
	v_mul_f32_e32 v9, v44, v9
	v_mul_f32_e32 v4, v45, v4
	v_mul_f32_e32 v5, v47, v5
	v_mul_f32_e32 v8, v8, v55
	v_mul_f32_e32 v10, v46, v10
	v_mul_f32_e32 v44, v52, v54
	v_cvt_pk_bf16_f32 v4, v9, v4
	v_cvt_pk_bf16_f32 v5, v10, v5
	v_cvt_pk_bf16_f32 v6, v44, v6
	v_cvt_pk_bf16_f32 v7, v8, v7
	v_mad_i64_i32 v[8:9], s[18:19], v129, s68, v[28:29]
	v_lshl_add_u64 v[8:9], v[8:9], 0, v[184:185]
	global_store_dwordx4 v[8:9], v[4:7], off offset:2048
	s_nop 1
	v_mov_b32_e32 v44, v183
	s_nop 0
	s_nop 1
	v_mov_b32_e32 v4, v186
	v_mov_b32_e32 v5, v187
	v_mov_b32_e32 v6, v188
	v_mov_b32_e32 v7, v189
	v_mov_b32_e32 v8, v190
	v_mov_b32_e32 v9, v191
	v_mov_b32_e32 v10, v192
	v_mov_b32_e32 v11, v193
	v_pk_mul_f32 v[30:31], v[30:31], v[8:9]
	s_nop 0
	v_add_f32_e32 v30, v44, v30
	v_add_f32_e32 v45, v30, v31
	v_pk_mul_f32 v[30:31], v[88:89], v[8:9]
	s_nop 0
	v_add_f32_e32 v30, v44, v30
	v_add_f32_e32 v46, v30, v31
	v_pk_mul_f32 v[30:31], v[90:91], v[8:9]
	s_nop 0
	v_add_f32_e32 v30, v44, v30
	v_add_f32_e32 v47, v30, v31
	v_pk_mul_f32 v[30:31], v[92:93], v[8:9]
	s_nop 0
	v_add_f32_e32 v30, v44, v30
	v_add_f32_e32 v52, v30, v31
	v_pk_mul_f32 v[30:31], v[94:95], v[8:9]
	s_nop 0
	v_add_f32_e32 v30, v44, v30
	v_add_f32_e32 v53, v30, v31
	v_pk_mul_f32 v[30:31], v[108:109], v[8:9]
	s_nop 0
	v_add_f32_e32 v30, v44, v30
	v_add_f32_e32 v54, v30, v31
	v_pk_mul_f32 v[30:31], v[110:111], v[8:9]
	v_pk_mul_f32 v[8:9], v[112:113], v[8:9]
	v_add_f32_e32 v30, v44, v30
	v_add_f32_e32 v8, v44, v8
	v_add_f32_e32 v30, v30, v31
	v_add_f32_e32 v31, v8, v9
	v_pk_mul_f32 v[8:9], v[20:21], v[10:11]
	s_nop 0
	v_add_f32_e32 v8, v45, v8
	v_add_f32_e32 v20, v8, v9
	v_pk_mul_f32 v[8:9], v[22:23], v[10:11]
	s_nop 0
	v_add_f32_e32 v8, v46, v8
	v_add_f32_e32 v21, v8, v9
	v_pk_mul_f32 v[8:9], v[24:25], v[10:11]
	s_nop 0
	v_add_f32_e32 v8, v47, v8
	v_add_f32_e32 v22, v8, v9
	v_pk_mul_f32 v[8:9], v[26:27], v[10:11]
	s_nop 0
	v_add_f32_e32 v8, v52, v8
	v_add_f32_e32 v23, v8, v9
	v_pk_mul_f32 v[8:9], v[60:61], v[10:11]
	s_nop 0
	v_add_f32_e32 v8, v53, v8
	v_add_f32_e32 v24, v8, v9
	v_pk_mul_f32 v[8:9], v[100:101], v[10:11]
	s_nop 0
	v_add_f32_e32 v8, v54, v8
	v_add_f32_e32 v25, v8, v9
	v_pk_mul_f32 v[8:9], v[36:37], v[10:11]
	s_nop 0
	v_add_f32_e32 v8, v30, v8
	v_add_f32_e32 v26, v8, v9
	v_pk_mul_f32 v[8:9], v[38:39], v[10:11]
	s_nop 0
	v_add_f32_e32 v8, v31, v8
	v_add_f32_e32 v10, v8, v9
	v_pk_mul_f32 v[8:9], v[12:13], v[4:5]
	s_nop 0
	v_add_f32_e32 v8, v20, v8
	v_add_f32_e32 v11, v8, v9
	v_pk_mul_f32 v[8:9], v[14:15], v[4:5]
	s_nop 0
	v_add_f32_e32 v8, v21, v8
	v_add_f32_e32 v12, v8, v9
	v_pk_mul_f32 v[8:9], v[16:17], v[4:5]
	s_nop 0
	v_add_f32_e32 v8, v22, v8
	v_add_f32_e32 v13, v8, v9
	v_pk_mul_f32 v[8:9], v[18:19], v[4:5]
	s_nop 0
	v_add_f32_e32 v8, v23, v8
	v_add_f32_e32 v14, v8, v9
	v_pk_mul_f32 v[8:9], v[64:65], v[4:5]
	s_nop 0
	v_add_f32_e32 v8, v24, v8
	v_add_f32_e32 v15, v8, v9
	v_pk_mul_f32 v[8:9], v[80:81], v[4:5]
	s_nop 0
	v_add_f32_e32 v8, v25, v8
	v_add_f32_e32 v16, v8, v9
	v_pk_mul_f32 v[8:9], v[56:57], v[4:5]
	v_pk_mul_f32 v[4:5], v[58:59], v[4:5]
	v_add_f32_e32 v8, v26, v8
	v_add_f32_e32 v4, v10, v4
	v_add_f32_e32 v8, v8, v9
	v_add_f32_e32 v9, v4, v5
	v_mov_b32_e32 v4, v43
	v_mov_b32_e32 v5, v35
	v_pk_mul_f32 v[4:5], v[4:5], v[6:7]
	v_mov_b32_e32 v43, v34
	v_add_f32_e32 v4, v11, v4
	v_add_f32_e32 v10, v4, v5
	v_mov_b32_e32 v4, v48
	v_mov_b32_e32 v5, v68
	v_pk_mul_f32 v[4:5], v[4:5], v[6:7]
	v_mov_b32_e32 v68, v49
	v_add_f32_e32 v4, v12, v4
	v_add_f32_e32 v11, v4, v5
	v_pk_mul_f32 v[4:5], v[68:69], v[6:7]
	s_nop 0
	v_add_f32_e32 v4, v13, v4
	v_add_f32_e32 v12, v4, v5
	v_mov_b32_e32 v4, v50
	v_mov_b32_e32 v5, v70
	v_pk_mul_f32 v[4:5], v[4:5], v[6:7]
	v_mov_b32_e32 v70, v51
	v_add_f32_e32 v4, v14, v4
	v_add_f32_e32 v13, v4, v5
	v_pk_mul_f32 v[4:5], v[70:71], v[6:7]
	s_nop 0
	v_add_f32_e32 v4, v15, v4
	v_add_f32_e32 v14, v4, v5
	v_mov_b32_e32 v4, v40
	v_mov_b32_e32 v5, v32
	v_pk_mul_f32 v[4:5], v[4:5], v[6:7]
	v_mov_b32_e32 v32, v41
	v_add_f32_e32 v4, v16, v4
	v_add_f32_e32 v15, v4, v5
	v_pk_mul_f32 v[4:5], v[32:33], v[6:7]
	s_nop 0
	v_add_f32_e32 v4, v8, v4
	v_add_f32_e32 v8, v4, v5
	v_pk_mul_f32 v[4:5], v[42:43], v[6:7]
	v_lshlrev_b32_e32 v6, 16, v1
	v_add_f32_e32 v4, v9, v4
	v_add_f32_e32 v4, v4, v5
	v_lshlrev_b32_e32 v5, 16, v0
	v_and_b32_e32 v0, 0xffff0000, v0
	v_and_b32_e32 v1, 0xffff0000, v1
	v_lshlrev_b32_e32 v7, 16, v2
	v_and_b32_e32 v2, 0xffff0000, v2
	v_lshlrev_b32_e32 v9, 16, v3
	v_and_b32_e32 v3, 0xffff0000, v3
	v_mul_f32_e32 v5, v11, v5
	v_mul_f32_e32 v0, v12, v0
	v_mul_f32_e32 v1, v14, v1
	v_mul_f32_e32 v2, v8, v2
	v_mul_f32_e32 v4, v4, v9
	v_mul_f32_e32 v3, v10, v3
	v_mul_f32_e32 v6, v13, v6
	v_mul_f32_e32 v7, v15, v7
	v_cvt_pk_bf16_f32 v0, v5, v0
	v_cvt_pk_bf16_f32 v1, v6, v1
	v_cvt_pk_bf16_f32 v2, v7, v2
	v_cvt_pk_bf16_f32 v3, v4, v3
	v_mad_i64_i32 v[4:5], s[18:19], v128, s68, v[28:29]
	v_lshl_add_u64 v[4:5], v[4:5], 0, v[184:185]
	global_store_dwordx4 v[4:5], v[0:3], off offset:2048
	s_mov_b64 s[18:19], 0
